# v37 + FoX main loop: next step's global tile loads and their scalar setup also issued before the step barrier; loop-back edge jumps straight behind the hoisted reads
# speedup vs baseline: 1.0030x; 1.0005x over previous
.LBB0_345:
	s_and_b64 vcc, exec, s[48:49]
	s_cbranch_vccnz .LBB0_347
	s_add_i32 s4, s90, 64
	s_ashr_i32 s5, s4, 31
	s_lshl_b64 s[4:5], s[4:5], 7
	v_lshl_add_u64 v[238:239], v[132:133], 0, s[4:5]
	global_load_dwordx4 v[100:103], v[238:239], off

.LBB0_349:
	ds_read_b128 v[60:63], v192 offset:96
	ds_read_b128 v[56:59], v192 offset:64
	ds_read_b128 v[48:51], v192
	ds_read_b128 v[52:55], v192 offset:32
	ds_read_b128 v[242:245], v189 offset:60416
	ds_read_b128 v[32:35], v192 offset:128
	ds_read_b128 v[36:39], v192 offset:160
	ds_read_b128 v[40:43], v192 offset:192
	ds_read_b128 v[44:47], v192 offset:224
	ds_read_b128 v[250:253], v189 offset:61440
	s_waitcnt lgkmcnt(10)
	s_barrier
	v_add_u32_e32 v196, s64, v144
	ds_read_b128 v[238:241], v196
	ds_read_b128 v[246:249], v196 offset:512
	s_waitcnt lgkmcnt(1)
	v_mfma_f32_32x32x16_bf16 v[48:63], v[238:241], v[242:245], v[48:63]
	ds_read_b128 v[238:241], v196 offset:2080
	v_max3_f32 v237, v80, s94, v81
	v_max3_f32 v237, v237, v82, v83
	v_add_f32_e32 v198, 0, v198
	v_add_f32_e32 v198, v199, v198
	v_add_f32_e32 v198, v200, v198
	v_add_f32_e32 v198, v201, v198
	v_add_f32_e32 v198, v202, v198
	s_waitcnt lgkmcnt(1)
	v_mfma_f32_32x32x16_bf16 v[32:47], v[246:249], v[242:245], v[32:47]
	ds_read_b128 v[242:245], v196 offset:2592
	ds_read_b128 v[246:249], v189 offset:62464
	v_max3_f32 v237, v237, v84, v85
	v_max3_f32 v237, v237, v86, v87
	v_add_f32_e32 v198, v203, v198
	v_add_f32_e32 v198, v204, v198
	v_add_f32_e32 v198, v205, v198
	v_add_f32_e32 v198, v206, v198
	v_add_f32_e32 v198, v207, v198
	s_waitcnt lgkmcnt(2)
	v_mfma_f32_32x32x16_bf16 v[48:63], v[238:241], v[250:253], v[48:63]
	ds_read_b128 v[238:241], v196 offset:4160
	v_max3_f32 v237, v237, v88, v89
	v_max3_f32 v237, v237, v90, v91
	v_add_f32_e32 v198, v208, v198
	v_add_f32_e32 v198, v209, v198
	v_add_f32_e32 v198, v210, v198
	v_add_f32_e32 v198, v211, v198
	v_add_f32_e32 v198, v212, v198
	s_waitcnt lgkmcnt(2)
	v_mfma_f32_32x32x16_bf16 v[32:47], v[242:245], v[250:253], v[32:47]
	ds_read_b128 v[242:245], v196 offset:4672
	ds_read_b128 v[250:253], v189 offset:63488
	v_max3_f32 v237, v237, v92, v93
	v_max3_f32 v237, v237, v94, v95
	v_add_f32_e32 v198, v213, v198
	v_add_f32_e32 v198, v214, v198
	v_add_f32_e32 v198, v215, v198
	v_add_f32_e32 v198, v216, v198
	v_add_f32_e32 v198, v217, v198
	s_waitcnt lgkmcnt(2)
	v_mfma_f32_32x32x16_bf16 v[48:63], v[238:241], v[246:249], v[48:63]
	ds_read_b128 v[238:241], v196 offset:6240
	v_max3_f32 v237, v237, v64, v65
	v_max3_f32 v237, v237, v66, v67
	v_add_f32_e32 v198, v218, v198
	v_add_f32_e32 v198, v219, v198
	v_add_f32_e32 v198, v220, v198
	v_add_f32_e32 v198, v221, v198
	v_add_f32_e32 v198, v222, v198
	s_waitcnt lgkmcnt(2)
	v_mfma_f32_32x32x16_bf16 v[32:47], v[242:245], v[246:249], v[32:47]
	ds_read_b128 v[242:245], v196 offset:6752
	v_max3_f32 v237, v237, v68, v69
	v_max3_f32 v237, v237, v70, v71
	v_add_f32_e32 v198, v223, v198
	v_add_f32_e32 v198, v224, v198
	v_add_f32_e32 v198, v225, v198
	v_add_f32_e32 v198, v226, v198
	v_add_f32_e32 v198, v227, v198
	s_waitcnt lgkmcnt(1)
	v_mfma_f32_32x32x16_bf16 v[48:63], v[238:241], v[250:253], v[48:63]
	v_max3_f32 v196, v237, v72, v73
	v_max3_f32 v196, v196, v74, v75
	v_add_f32_e32 v198, v228, v198
	v_add_f32_e32 v198, v229, v198
	v_fmac_f32_e32 v198, v191, v197
	s_waitcnt lgkmcnt(0)
	v_mfma_f32_32x32x16_bf16 v[32:47], v[242:245], v[250:253], v[32:47]
	v_max3_f32 v196, v196, v76, v77
	v_max3_f32 v196, v196, v78, v79
	v_mov_b32_e32 v237, v196
	v_mov_b32_e32 v238, v196
	s_nop 1
	v_permlane32_swap_b32_e32 v237, v238
	v_cndmask_b32_e64 v237, v237, v238, s[36:37]
	v_max_f32_e32 v237, v237, v237
	v_max_f32_e32 v196, v196, v237
	v_add_f32_e32 v237, 0x40c00000, v236
	v_cmp_gt_f32_e32 vcc, v196, v237
	s_nop 1
	v_cndmask_b32_e32 v196, v236, v196, vcc
	v_sub_f32_e32 v237, v236, v196
	v_exp_f32_e32 v237, v237
	v_cmp_neq_f32_e32 vcc, v196, v236
	s_cbranch_vccz .LBB0_353
	s_and_saveexec_b64 vcc, s[36:37]
	ds_write_b32 v176, v237 offset:58112
	s_or_b64 exec, exec, vcc
	v_add_u32_e32 v236, s75, v108
	ds_read_b128 v[238:241], v236 offset:58208
	ds_read_b128 v[242:245], v236 offset:58176
	ds_read_b128 v[246:249], v236 offset:58144
	ds_read_b128 v[250:253], v236 offset:58112
	s_waitcnt lgkmcnt(3)
	v_pk_mul_f32 v[12:13], v[12:13], v[238:239]
	s_waitcnt lgkmcnt(2)
	v_pk_mul_f32 v[8:9], v[8:9], v[242:243]
	s_waitcnt lgkmcnt(1)
	v_pk_mul_f32 v[4:5], v[4:5], v[246:247]
	v_pk_mul_f32 v[14:15], v[14:15], v[240:241]
	v_pk_mul_f32 v[10:11], v[10:11], v[244:245]
	v_pk_mul_f32 v[6:7], v[6:7], v[248:249]
	s_waitcnt lgkmcnt(0)
	v_pk_mul_f32 v[2:3], v[2:3], v[252:253]
	v_pk_mul_f32 v[0:1], v[0:1], v[250:251]
	v_pk_mul_f32 v[28:29], v[28:29], v[238:239]
	v_pk_mul_f32 v[24:25], v[24:25], v[242:243]
	v_pk_mul_f32 v[20:21], v[20:21], v[246:247]
	v_pk_mul_f32 v[30:31], v[30:31], v[240:241]
	v_pk_mul_f32 v[26:27], v[26:27], v[244:245]
	v_pk_mul_f32 v[22:23], v[22:23], v[248:249]
	v_pk_mul_f32 v[18:19], v[18:19], v[252:253]
	v_pk_mul_f32 v[16:17], v[16:17], v[250:251]

.LBB0_357:
	v_add_f32_e32 v80, 0, v80
	v_add_f32_e32 v80, v81, v80
	v_add_f32_e32 v80, v82, v80
	v_add_f32_e32 v80, v83, v80
	v_add_f32_e32 v80, v84, v80
	v_add_f32_e32 v80, v85, v80
	v_add_f32_e32 v80, v86, v80
	v_add_f32_e32 v80, v87, v80
	v_add_f32_e32 v80, v88, v80
	v_add_f32_e32 v80, v89, v80
	v_add_f32_e32 v80, v90, v80
	v_add_f32_e32 v80, v91, v80
	v_add_f32_e32 v80, v92, v80
	v_add_f32_e32 v80, v93, v80
	v_add_f32_e32 v80, v94, v80
	v_add_f32_e32 v80, v95, v80
	v_add_f32_e32 v64, v64, v80
	v_add_f32_e32 v64, v65, v64
	v_add_f32_e32 v64, v66, v64
	v_add_f32_e32 v64, v67, v64
	v_add_f32_e32 v64, v68, v64
	v_add_f32_e32 v64, v69, v64
	v_add_f32_e32 v64, v70, v64
	v_add_f32_e32 v64, v71, v64
	v_add_f32_e32 v64, v72, v64
	v_add_f32_e32 v64, v73, v64
	v_add_f32_e32 v64, v74, v64
	v_add_f32_e32 v64, v75, v64
	v_add_f32_e32 v64, v76, v64
	v_add_f32_e32 v64, v77, v64
	v_add_f32_e32 v64, v78, v64
	v_add_f32_e32 v191, v79, v64
	s_addk_i32 s90, 0xff80
	s_add_i32 s4, s56, 1
	v_fmac_f32_e32 v191, v198, v237
	s_cmp_lt_u32 s4, s55
	v_add_u32_e32 v192, 0xfffffe00, v192
	s_cbranch_scc0 .Lfx_exit
	s_mov_b32 s57, s56
	s_add_i32 s4, s90, 0x80
	s_ashr_i32 s5, s4, 31
	s_lshl_b64 s[4:5], s[4:5], 7
	v_lshl_add_u64 v[198:199], v[132:133], 0, s[4:5]
	global_load_dwordx4 v[100:103], v[198:199], off
	s_add_i32 s56, s57, 2
	s_cmp_lt_u32 s56, s55
	s_cselect_b64 s[4:5], -1, 0
	s_cmp_ge_u32 s56, s55
	s_cbranch_scc1 .Lfx_h2
	s_add_i32 s48, s90, 64
	s_ashr_i32 s49, s48, 31
	s_lshl_b64 s[48:49], s[48:49], 7
	v_lshl_add_u64 v[198:199], v[130:131], 0, s[48:49]
	global_load_dwordx4 v[96:99], v[198:199], off
.Lfx_h2:
	ds_read_b128 v[92:95], v192 offset:352
	ds_read_b128 v[88:91], v192 offset:320
	ds_read_b128 v[80:83], v192 offset:256
	ds_read_b128 v[84:87], v192 offset:288
	ds_read_b128 v[202:205], v189 offset:60416
	ds_read_b128 v[64:67], v192 offset:384
	ds_read_b128 v[68:71], v192 offset:416
	ds_read_b128 v[72:75], v192 offset:448
	ds_read_b128 v[76:79], v192 offset:480
	ds_read_b128 v[210:213], v189 offset:61440
	s_waitcnt lgkmcnt(10)
	s_barrier
	s_branch .Lfx_hoisted_8013
